# speedup vs baseline: 1.0052x; 1.0052x over previous
; template <int KS, bool SAFE> __device__ __forceinline__ void fused_ks(f32x16* o, f32x16& lacc, int vb, const VFrag& cur, VFrag& nxt, f32x16& p0, f32x16& p1, float& ps, ...
;   if constexpr (KS < 3) { vfrag_issue<KS + 1>(nxt, vb); asm volatile("s_waitcnt lgkmcnt(8)" ::: "memory"); }
;   else asm volatile("s_waitcnt lgkmcnt(0)" ::: "memory");
;   const bf16x8 pa = (KS == 0) ? pa0 : (KS == 1) ? pa1 : (KS == 2) ? pa2 : pa3;
;   SBAR();
;   o[0] = MFMA32(pa, PKV(cur.l0, cur.h0), o[0]); SBAR(); sm1_chunk<KS * 4 + 0>(p0, p1); if constexpr (KS > 0) SM2_UNIT(2 * KS - 1); SBAR();
;   o[1] = MFMA32(pa, PKV(cur.l1, cur.h1), o[1]); SBAR(); sm1_chunk<KS * 4 + 1>(p0, p1);
;   if (dow) {
;     if constexpr (KS == 0) { asm volatile("s_waitcnt vmcnt(0)" ::: "memory"); *reinterpret_cast<bf16x8*>(sd.k0) = st.ks0; }
;     else if constexpr (KS == 1) *reinterpret_cast<bf16x8*>(sd.k1) = st.ks1;
;     else if constexpr (KS == 2) *reinterpret_cast<bf16x8*>(sd.v0) = st.vs0;
;     else *reinterpret_cast<bf16x8*>(sd.v1) = st.vs1;
;   }
;   SBAR();
;   o[2] = MFMA32(pa, PKV(cur.l2, cur.h2), o[2]); SBAR(); sm1_chunk<KS * 4 + 2>(p0, p1); SM2_UNIT(2 * KS); SBAR();
;   o[3] = MFMA32(pa, PKV(cur.l3, cur.h3), o[3]); SBAR(); sm1_chunk<KS * 4 + 3>(p0, p1); SBAR();
;   if constexpr (!SAFE) { lacc = MFMA32(pa, ones, lacc); SBAR(); }
; }
; template <bool SAFE> ...
;   bf16x8 kb[8];
; #pragma unroll
;   for (int d0 = 0; d0 < 4; ++d0) { const int cb = (cb0 + d0 * 16 + hi * 8) * 2;
;     kb[2 * d0] = *reinterpret_cast<const bf16x8*>((const char*)Ks + KSWZ(r32, cb));
;     kb[2 * d0 + 1] = *reinterpret_cast<const bf16x8*>((const char*)Ks + KSWZ(32 + r32, cb)); }
;   VFrag fa, fb;
;   vfrag_issue<0>(fa, vb);
;   p0 = MFMA32(kb[0], qr[0], cinit); p1 = MFMA32(kb[1], qr[0], cinit);
; #pragma unroll
;   for (int d0 = 1; d0 < 4; ++d0) { p0 = MFMA32(kb[2 * d0], qr[d0], p0); p1 = MFMA32(kb[2 * d0 + 1], qr[d0], p1); }
;   SBAR();
;   unsigned a0, a1, b0, b1; ps = 0.f;
;   fused_ks<0, SAFE>(o, lacc, vb, fa, fb, p0, p1, ps, a0, a1, b0, b1, pa0, pa1, pa2, pa3, st, sd, dow, ones);
;   fused_ks<1, SAFE>(o, lacc, vb, fb, fa, p0, p1, ps, a0, a1, b0, b1, pa0, pa1, pa2, pa3, st, sd, dow, ones);
;   fused_ks<2, SAFE>(o, lacc, vb, fa, fb, p0, p1, ps, a0, a1, b0, b1, pa0, pa1, pa2, pa3, st, sd, dow, ones);
;   fused_ks<3, SAFE>(o, lacc, vb, fb, fa, p0, p1, ps, a0, a1, b0, b1, pa0, pa1, pa2, pa3, st, sd, dow, ones);
.LBB0_105:
	ds_read_b128 v[212:215], v77 offset:49152
	ds_read_b128 v[216:219], v77 offset:57344
	s_lshl_b32 s7, s6, 14
	s_add_i32 s66, s7, 0
	s_add_i32 s98, s5, 2
	s_min_i32 s98, s98, s93
	s_mul_i32 s98, s98, 0x60000
	s_add_u32 s98, s10, s98
	s_addc_u32 s99, s11, 0
	s_add_u32 s100, s98, 0x30000
	s_addc_u32 s101, s99, 0
	v_add_u32_e32 v78, s66, v209
	v_mfma_f32_32x32x16_bf16 v[112:127], v[68:71], v[132:135], v[80:95]
	v_add_u32_e32 v160, s66, v210
	v_lshl_add_u32 v194, s4, 14, v211
	s_mov_b32 s8, s9
	s_lshl_b32 s9, s9, 14
	s_add_i32 s9, s9, 0
	v_add_u32_e32 v76, s9, v207
	v_mfma_f32_32x32x16_bf16 v[96:111], v[72:75], v[132:135], v[80:95]
	ds_read_b128 v[68:71], v78 offset:49152
	ds_read_b128 v[72:75], v78 offset:57344
	v_add_u32_e32 v188, s9, v205
	v_add_u32_e32 v161, s9, v203
	v_add_u32_e32 v170, s9, v204
	v_mfma_f32_16x16x32_bf16 v[64:67], v[180:183], v[148:151], v[64:67]
	s_waitcnt lgkmcnt(3)
	v_mfma_f32_32x32x16_bf16 v[112:127], v[212:215], v[136:139], v[112:127]
	ds_read_b128 v[212:215], v160 offset:49152
	s_waitcnt vmcnt(3)
	ds_write_b128 v161, v[166:169] offset:49152
	global_load_dwordx4 v[166:169], v247, s[98:99] offset:1024
	s_waitcnt lgkmcnt(4)
	v_mfma_f32_32x32x16_bf16 v[96:111], v[216:219], v[136:139], v[96:111]
	ds_read_b128 v[216:219], v160 offset:57344
	v_add_u32_e32 v189, s9, v206
	v_add_u32_e32 v77, s9, v208
	v_mfma_f32_16x16x32_bf16 v[64:67], v[184:187], v[148:151], v[64:67]
	s_waitcnt lgkmcnt(4)
	v_mfma_f32_32x32x16_bf16 v[112:127], v[68:71], v[140:143], v[112:127]
	ds_read_b64_tr_b16 v[220:221], v194 offset:0
	ds_read_b64_tr_b16 v[222:223], v194 offset:0x800
	s_waitcnt vmcnt(3)
	ds_write_b128 v170, v[162:165] offset:49152
	global_load_dwordx4 v[162:165], v247, s[100:101] offset:1024
	v_mfma_f32_16x16x32_bf16 v[64:67], v[176:179], v[148:151], v[64:67]
	s_waitcnt lgkmcnt(6)
	v_mfma_f32_32x32x16_bf16 v[96:111], v[72:75], v[140:143], v[96:111]
	v_mfma_f32_16x16x32_bf16 v[64:67], v[172:175], v[148:151], v[64:67]
	s_waitcnt lgkmcnt(5)
	v_mfma_f32_32x32x16_bf16 v[112:127], v[212:215], v[144:147], v[112:127]
	ds_read_b64_tr_b16 v[212:213], v194 offset:0x200
	ds_read_b64_tr_b16 v[214:215], v194 offset:0xa00
	ds_read_b64_tr_b16 v[224:225], v194 offset:0x400
	ds_read_b64_tr_b16 v[226:227], v194 offset:0xc00
	ds_read_b64_tr_b16 v[228:229], v194 offset:0x600
	ds_read_b64_tr_b16 v[230:231], v194 offset:0xe00
	s_waitcnt lgkmcnt(7)
	v_mfma_f32_32x32x16_bf16 v[96:111], v[216:219], v[144:147], v[96:111]
	ds_read_b64_tr_b16 v[216:217], v194 offset:0x1000
	ds_read_b64_tr_b16 v[218:219], v194 offset:0x1800
	ds_read_b64_tr_b16 v[232:233], v194 offset:0x1200
	ds_read_b64_tr_b16 v[234:235], v194 offset:0x1a00
	ds_read_b64_tr_b16 v[236:237], v194 offset:0x1400
	ds_read_b64_tr_b16 v[238:239], v194 offset:0x1c00
	ds_read_b64_tr_b16 v[240:241], v194 offset:0x1600
	ds_read_b64_tr_b16 v[242:243], v194 offset:0x1e00
	s_nop 0
	v_mfma_f32_32x32x16_bf16 v[48:63], v[180:183], v[220:223], v[48:63]
	s_nop 0
	v_exp_f32_e32 v112, v112
	v_exp_f32_e32 v113, v113
	s_waitcnt lgkmcnt(12)
	v_mfma_f32_32x32x16_bf16 v[32:47], v[180:183], v[212:215], v[32:47]
	v_exp_f32_e32 v114, v114
	v_exp_f32_e32 v115, v115
	s_waitcnt lgkmcnt(10)
	v_mfma_f32_32x32x16_bf16 v[0:15], v[180:183], v[224:227], v[0:15]
	v_exp_f32_e32 v171, v116
	v_exp_f32_e32 v220, v117
	s_waitcnt lgkmcnt(8)
	v_mfma_f32_32x32x16_bf16 v[16:31], v[180:183], v[228:231], v[16:31]
	v_exp_f32_e32 v221, v118
	v_exp_f32_e32 v222, v119
	v_cvt_pk_bf16_f32 v180, v112, v113
	v_cvt_pk_bf16_f32 v181, v114, v115
	ds_read_b64_tr_b16 v[112:113], v194 offset:0x2000
	ds_read_b64_tr_b16 v[114:115], v194 offset:0x2800
	ds_read_b64_tr_b16 v[116:117], v194 offset:0x2200
	ds_read_b64_tr_b16 v[118:119], v194 offset:0x2a00
	ds_read_b64_tr_b16 v[248:249], v194 offset:0x2400
	ds_read_b64_tr_b16 v[250:251], v194 offset:0x2c00
	ds_read_b64_tr_b16 v[212:213], v194 offset:0x2600
	ds_read_b64_tr_b16 v[214:215], v194 offset:0x2e00
	s_waitcnt lgkmcnt(8)
	v_mfma_f32_32x32x16_bf16 v[48:63], v[184:187], v[216:219], v[48:63]
	v_cvt_pk_bf16_f32 v182, v171, v220
	v_cvt_pk_bf16_f32 v183, v221, v222
	v_exp_f32_e32 v120, v120
	v_exp_f32_e32 v121, v121
	v_mfma_f32_32x32x16_bf16 v[32:47], v[184:187], v[232:235], v[32:47]
	v_exp_f32_e32 v122, v122
	v_exp_f32_e32 v123, v123
	v_mfma_f32_32x32x16_bf16 v[0:15], v[184:187], v[236:239], v[0:15]
	v_exp_f32_e32 v160, v124
	v_exp_f32_e32 v161, v125
	v_mfma_f32_32x32x16_bf16 v[16:31], v[184:187], v[240:243], v[16:31]
	v_exp_f32_e32 v220, v126
	v_exp_f32_e32 v221, v127
	v_cvt_pk_bf16_f32 v184, v120, v121
	v_cvt_pk_bf16_f32 v185, v122, v123
	s_waitcnt lgkmcnt(0)
	s_barrier
; template <int KS, bool SAFE> __device__ __forceinline__ void fused_ks(f32x16* o, f32x16& lacc, int vb, const VFrag& cur, VFrag& nxt, f32x16& p0, f32x16& p1, float& ps, ...
;   if constexpr (KS < 3) { vfrag_issue<KS + 1>(nxt, vb); asm volatile("s_waitcnt lgkmcnt(8)" ::: "memory"); }
;   else asm volatile("s_waitcnt lgkmcnt(0)" ::: "memory");
;   const bf16x8 pa = (KS == 0) ? pa0 : (KS == 1) ? pa1 : (KS == 2) ? pa2 : pa3;
;   SBAR();
;   o[0] = MFMA32(pa, PKV(cur.l0, cur.h0), o[0]); SBAR(); sm1_chunk<KS * 4 + 0>(p0, p1); if constexpr (KS > 0) SM2_UNIT(2 * KS - 1); SBAR();
;   o[1] = MFMA32(pa, PKV(cur.l1, cur.h1), o[1]); SBAR(); sm1_chunk<KS * 4 + 1>(p0, p1);
;   if (dow) {
;     if constexpr (KS == 0) { asm volatile("s_waitcnt vmcnt(0)" ::: "memory"); *reinterpret_cast<bf16x8*>(sd.k0) = st.ks0; }
;     else if constexpr (KS == 1) *reinterpret_cast<bf16x8*>(sd.k1) = st.ks1;
;     else if constexpr (KS == 2) *reinterpret_cast<bf16x8*>(sd.v0) = st.vs0;
;     else *reinterpret_cast<bf16x8*>(sd.v1) = st.vs1;
;   }
;   SBAR();
;   o[2] = MFMA32(pa, PKV(cur.l2, cur.h2), o[2]); SBAR(); sm1_chunk<KS * 4 + 2>(p0, p1); SM2_UNIT(2 * KS); SBAR();
;   o[3] = MFMA32(pa, PKV(cur.l3, cur.h3), o[3]); SBAR(); sm1_chunk<KS * 4 + 3>(p0, p1); SBAR();
;   if constexpr (!SAFE) { lacc = MFMA32(pa, ones, lacc); SBAR(); }
; }
; template <bool SAFE> ...
;   bf16x8 kb[8];
; #pragma unroll
;   for (int d0 = 0; d0 < 4; ++d0) { const int cb = (cb0 + d0 * 16 + hi * 8) * 2;
;     kb[2 * d0] = *reinterpret_cast<const bf16x8*>((const char*)Ks + KSWZ(r32, cb));
;     kb[2 * d0 + 1] = *reinterpret_cast<const bf16x8*>((const char*)Ks + KSWZ(32 + r32, cb)); }
;   VFrag fa, fb;
;   vfrag_issue<0>(fa, vb);
;   p0 = MFMA32(kb[0], qr[0], cinit); p1 = MFMA32(kb[1], qr[0], cinit);
; #pragma unroll
;   for (int d0 = 1; d0 < 4; ++d0) { p0 = MFMA32(kb[2 * d0], qr[d0], p0); p1 = MFMA32(kb[2 * d0 + 1], qr[d0], p1); }
;   SBAR();
;   unsigned a0, a1, b0, b1; ps = 0.f;
;   fused_ks<0, SAFE>(o, lacc, vb, fa, fb, p0, p1, ps, a0, a1, b0, b1, pa0, pa1, pa2, pa3, st, sd, dow, ones);
;   fused_ks<1, SAFE>(o, lacc, vb, fb, fa, p0, p1, ps, a0, a1, b0, b1, pa0, pa1, pa2, pa3, st, sd, dow, ones);
;   fused_ks<2, SAFE>(o, lacc, vb, fa, fb, p0, p1, ps, a0, a1, b0, b1, pa0, pa1, pa2, pa3, st, sd, dow, ones);
;   fused_ks<3, SAFE>(o, lacc, vb, fb, fa, p0, p1, ps, a0, a1, b0, b1, pa0, pa1, pa2, pa3, st, sd, dow, ones);
	v_mfma_f32_32x32x16_bf16 v[48:63], v[176:179], v[112:115], v[48:63]
	ds_read_b128 v[68:71], v76 offset:49152
	ds_read_b128 v[72:75], v76 offset:57344
	ds_read_b64_tr_b16 v[120:121], v194 offset:0x3000
	ds_read_b64_tr_b16 v[122:123], v194 offset:0x3800
	ds_read_b64_tr_b16 v[124:125], v194 offset:0x3200
	ds_read_b64_tr_b16 v[126:127], v194 offset:0x3a00
	ds_read_b64_tr_b16 v[252:253], v194 offset:0x3400
	ds_read_b64_tr_b16 v[254:255], v194 offset:0x3c00
	ds_read_b64_tr_b16 v[216:217], v194 offset:0x3600
	ds_read_b64_tr_b16 v[218:219], v194 offset:0x3e00
	v_cvt_pk_bf16_f32 v186, v160, v161
	v_cvt_pk_bf16_f32 v187, v220, v221
	v_exp_f32_e32 v96, v96
	v_exp_f32_e32 v97, v97
	v_mfma_f32_32x32x16_bf16 v[32:47], v[176:179], v[116:119], v[32:47]
	v_exp_f32_e32 v98, v98
	v_exp_f32_e32 v99, v99
	s_waitcnt vmcnt(3)
	ds_write_b128 v188, v[156:159]
	global_load_dwordx4 v[156:159], v247, s[98:99] offset:2048
	v_mfma_f32_32x32x16_bf16 v[0:15], v[176:179], v[248:251], v[0:15]
	v_exp_f32_e32 v100, v100
	v_exp_f32_e32 v101, v101
	v_mfma_f32_32x32x16_bf16 v[16:31], v[176:179], v[212:215], v[16:31]
	v_cvt_pk_bf16_f32 v176, v96, v97
	v_cvt_pk_bf16_f32 v177, v98, v99
	v_exp_f32_e32 v96, v102
	v_exp_f32_e32 v97, v103
	s_waitcnt lgkmcnt(1)
	v_mfma_f32_32x32x16_bf16 v[48:63], v[172:175], v[120:123], v[48:63]
	v_cvt_pk_bf16_f32 v178, v100, v101
	v_cvt_pk_bf16_f32 v179, v96, v97
	v_exp_f32_e32 v98, v104
	v_exp_f32_e32 v99, v105
	v_mfma_f32_32x32x16_bf16 v[32:47], v[172:175], v[124:127], v[32:47]
	v_exp_f32_e32 v96, v106
	v_exp_f32_e32 v97, v107
	s_waitcnt vmcnt(3)
	ds_write_b128 v189, v[152:155]
	global_load_dwordx4 v[152:155], v247, s[100:101] offset:2048
	v_mfma_f32_32x32x16_bf16 v[0:15], v[172:175], v[252:255], v[0:15]
	v_exp_f32_e32 v100, v108
	v_exp_f32_e32 v101, v109
	v_mfma_f32_32x32x16_bf16 v[16:31], v[172:175], v[216:219], v[16:31]
	v_cvt_pk_bf16_f32 v172, v98, v99
	v_cvt_pk_bf16_f32 v173, v96, v97
	v_exp_f32_e32 v102, v110
	v_exp_f32_e32 v103, v111
	v_cvt_pk_bf16_f32 v174, v100, v101
	v_cvt_pk_bf16_f32 v175, v102, v103
	s_add_i32 s5, s5, 1
	s_mov_b32 s9, s4
	s_mov_b32 s4, s6
	s_cmp_lg_u32 s92, s5
	s_mov_b32 s6, s8
	s_cbranch_scc1 .LBB0_105
; #define MFMA32(a, b, c) __builtin_amdgcn_mfma_f32_32x32x16_bf16(a, b, c, 0, 0, 0)
; template <bool SAFE>
; __device__ __forceinline__ void diff_core(const bf16* __restrict__ Kh, const bf16* __restrict__ Vh, const int NT, const bf16x8* qr, char* lds,
;                                           const int wid, const int lane_unused, f32x16* o, f32x16& lacc, float& l_reg) {
;     ...
;   pv_d0(o, vb0 + bp * SHM_V, pa0, pa1, pa2, pa3);
;   if constexpr (!SAFE) {
;     lacc = MFMA32(pa0, ones, lacc); lacc = MFMA32(pa1, ones, lacc); lacc = MFMA32(pa2, ones, lacc); lacc = MFMA32(pa3, ones, lacc); }
; __device__ __forceinline__ void diff_attn_item(const bf16* __restrict__ qkv, bf16* __restrict__ mix, const float* __restrict__ dg,
;                                int tok0  , int key0  , int seq, int head, float lam, float oscale, const int W) {
;     ...
;     bool bad = (FORCE_SAFE != 0);
; #pragma unroll
;     for (int r = 0; r < 16; ++r) bad = bad || !(lacc[r] < 1.0e30f);
;     if (lane == 0) flag_l[wid] = __any(bad) ? 1 : 0;
	v_mov_b32_e32 v160, v180
	v_mov_b32_e32 v161, v181
	v_mov_b32_e32 v170, v184
	v_mov_b32_e32 v171, v185
	v_mov_b32_e32 v180, v176
	v_mov_b32_e32 v181, v177
	v_mov_b32_e32 v188, v172
	v_mov_b32_e32 v189, v173
	s_waitcnt vmcnt(0)
	v_add_u32_e32 v168, s7, v211
	ds_read_b64_tr_b16 v[80:81], v168 offset:0
	ds_read_b64_tr_b16 v[82:83], v168 offset:0x800
	ds_read_b64_tr_b16 v[84:85], v168 offset:0x1000
	ds_read_b64_tr_b16 v[86:87], v168 offset:0x1800
	ds_read_b64_tr_b16 v[88:89], v168 offset:0x2000
	ds_read_b64_tr_b16 v[90:91], v168 offset:0x2800
	ds_read_b64_tr_b16 v[92:93], v168 offset:0x3000
	ds_read_b64_tr_b16 v[94:95], v168 offset:0x3800
	s_waitcnt lgkmcnt(0)
	s_waitcnt vmcnt(0)
	v_mov_b32_e32 v162, v182
	v_mov_b32_e32 v163, v183
	v_mov_b32_e32 v172, v186
	v_mov_b32_e32 v173, v187
	v_mov_b32_e32 v182, v178
	v_mov_b32_e32 v183, v179
	v_mov_b32_e32 v190, v174
	v_mov_b32_e32 v191, v175
	ds_read_b64_tr_b16 v[96:97], v168 offset:0x200
	ds_read_b64_tr_b16 v[98:99], v168 offset:0xa00
	ds_read_b64_tr_b16 v[100:101], v168 offset:0x1200
	ds_read_b64_tr_b16 v[102:103], v168 offset:0x1a00
	ds_read_b64_tr_b16 v[104:105], v168 offset:0x2200
	ds_read_b64_tr_b16 v[106:107], v168 offset:0x2a00
	ds_read_b64_tr_b16 v[108:109], v168 offset:0x3200
	ds_read_b64_tr_b16 v[110:111], v168 offset:0x3a00
	s_waitcnt lgkmcnt(0)
	ds_read_b64_tr_b16 v[112:113], v168 offset:0x400
	ds_read_b64_tr_b16 v[114:115], v168 offset:0xc00
	ds_read_b64_tr_b16 v[116:117], v168 offset:0x1400
	ds_read_b64_tr_b16 v[118:119], v168 offset:0x1c00
	ds_read_b64_tr_b16 v[120:121], v168 offset:0x2400
	ds_read_b64_tr_b16 v[122:123], v168 offset:0x2c00
	ds_read_b64_tr_b16 v[124:125], v168 offset:0x3400
	ds_read_b64_tr_b16 v[126:127], v168 offset:0x3c00
	s_waitcnt lgkmcnt(0)
	ds_read_b64_tr_b16 v[152:153], v168 offset:0x600
	ds_read_b64_tr_b16 v[154:155], v168 offset:0xe00
	ds_read_b64_tr_b16 v[156:157], v168 offset:0x1600
	ds_read_b64_tr_b16 v[158:159], v168 offset:0x1e00
	ds_read_b64_tr_b16 v[164:165], v168 offset:0x2600
	ds_read_b64_tr_b16 v[166:167], v168 offset:0x2e00
	ds_read_b64_tr_b16 v[174:175], v168 offset:0x3600
	ds_read_b64_tr_b16 v[176:177], v168 offset:0x3e00
	s_waitcnt lgkmcnt(0)
	v_mfma_f32_16x16x32_bf16 v[64:67], v[160:163], v[148:151], v[64:67]
	v_cmp_eq_u32_e32 vcc, 0, v200
	v_mfma_f32_32x32x16_bf16 v[48:63], v[160:163], v[80:83], v[48:63]
	v_mfma_f32_32x32x16_bf16 v[32:47], v[160:163], v[96:99], v[32:47]
	v_mfma_f32_32x32x16_bf16 v[0:15], v[160:163], v[112:115], v[0:15]
	v_mfma_f32_32x32x16_bf16 v[16:31], v[160:163], v[152:155], v[16:31]
	v_mfma_f32_16x16x32_bf16 v[64:67], v[170:173], v[148:151], v[64:67]
	v_mfma_f32_32x32x16_bf16 v[48:63], v[170:173], v[84:87], v[48:63]
	v_mfma_f32_32x32x16_bf16 v[32:47], v[170:173], v[100:103], v[32:47]
	v_mfma_f32_32x32x16_bf16 v[0:15], v[170:173], v[116:119], v[0:15]
	v_mfma_f32_32x32x16_bf16 v[16:31], v[170:173], v[156:159], v[16:31]
	v_mfma_f32_16x16x32_bf16 v[64:67], v[180:183], v[148:151], v[64:67]
	v_mfma_f32_32x32x16_bf16 v[48:63], v[180:183], v[88:91], v[48:63]
	v_mfma_f32_32x32x16_bf16 v[32:47], v[180:183], v[104:107], v[32:47]
	v_mfma_f32_32x32x16_bf16 v[0:15], v[180:183], v[120:123], v[0:15]
	v_mfma_f32_32x32x16_bf16 v[16:31], v[180:183], v[164:167], v[16:31]
	v_mfma_f32_16x16x32_bf16 v[64:67], v[188:191], v[148:151], v[64:67]
	v_mfma_f32_32x32x16_bf16 v[48:63], v[188:191], v[92:95], v[48:63]
	v_mfma_f32_32x32x16_bf16 v[32:47], v[188:191], v[108:111], v[32:47]
	v_mfma_f32_32x32x16_bf16 v[0:15], v[188:191], v[124:127], v[0:15]
	v_mfma_f32_32x32x16_bf16 v[16:31], v[188:191], v[174:177], v[16:31]
	v_and_b32_e32 v248, 15, v200
	v_lshrrev_b32_e32 v249, 4, v200
	v_and_b32_e32 v250, 1, v200
	v_lshlrev_b32_e32 v249, 4, v249
	v_lshl_add_u32 v249, v250, 6, v249
	v_add_u32_e32 v249, s62, v249
	v_cmp_gt_u32_e64 s[98:99], 2, v248
	v_lshl_add_u32 v250, v198, 4, s62
	s_nop 7
	s_and_saveexec_b64 s[100:101], s[98:99]
	ds_write_b128 v249, v[64:67]
	s_mov_b64 exec, s[100:101]
	s_waitcnt lgkmcnt(0)
	ds_read_b128 v[64:67], v250
	ds_read_b128 v[68:71], v250 offset:32
	ds_read_b128 v[72:75], v250 offset:64
	ds_read_b128 v[76:79], v250 offset:96
	s_waitcnt lgkmcnt(0)
	s_and_saveexec_b64 s[6:7], vcc
	s_cbranch_execz .LBB0_108
	s_nop 5
	v_cmp_ngt_f32_e32 vcc, s85, v64
	v_cmp_ngt_f32_e64 s[4:5], s85, v65
	s_or_b64 s[4:5], vcc, s[4:5]
	v_cmp_ngt_f32_e32 vcc, s85, v66
	s_or_b64 s[4:5], s[4:5], vcc
	v_cmp_ngt_f32_e32 vcc, s85, v67
	s_or_b64 s[4:5], s[4:5], vcc
	v_cmp_ngt_f32_e32 vcc, s85, v68
	s_or_b64 s[4:5], s[4:5], vcc
	v_cmp_ngt_f32_e32 vcc, s85, v69
	s_or_b64 s[4:5], s[4:5], vcc
	v_cmp_ngt_f32_e32 vcc, s85, v70
	s_or_b64 s[4:5], s[4:5], vcc
	v_cmp_ngt_f32_e32 vcc, s85, v71
	s_or_b64 s[4:5], s[4:5], vcc
	v_cmp_ngt_f32_e32 vcc, s85, v72
	s_or_b64 s[4:5], s[4:5], vcc
	v_cmp_ngt_f32_e32 vcc, s85, v73
	s_or_b64 s[4:5], s[4:5], vcc
	v_cmp_ngt_f32_e32 vcc, s85, v74
	s_or_b64 s[4:5], s[4:5], vcc
	v_cmp_ngt_f32_e32 vcc, s85, v75
	s_or_b64 s[4:5], s[4:5], vcc
	v_cmp_ngt_f32_e32 vcc, s85, v76
	s_or_b64 s[4:5], s[4:5], vcc
	v_cmp_ngt_f32_e32 vcc, s85, v77
	s_or_b64 s[4:5], s[4:5], vcc
	v_cmp_ngt_f32_e32 vcc, s85, v78
	s_or_b64 s[4:5], s[4:5], vcc
	v_cmp_ngt_f32_e32 vcc, s85, v79
	s_or_b64 s[4:5], s[4:5], vcc
	v_cndmask_b32_e64 v80, 0, 1, s[4:5]
	v_cmp_ne_u32_e32 vcc, 0, v80
	s_cmp_lg_u64 vcc, 0
	s_cselect_b64 s[4:5], -1, 0
	v_cndmask_b32_e64 v80, 0, 1, s[4:5]
	v_readlane_b32 s4, v246, 17
	s_nop 1
	v_mov_b32_e32 v81, s4
	ds_write_b32 v81, v80

; template <int KS, bool SAFE> __device__ __forceinline__ void fused_ks(f32x16* o, f32x16& lacc, int vb, const VFrag& cur, VFrag& nxt, f32x16& p0, f32x16& p1, float& ps, ...
;   if constexpr (KS < 3) { vfrag_issue<KS + 1>(nxt, vb); asm volatile("s_waitcnt lgkmcnt(8)" ::: "memory"); }
;   else asm volatile("s_waitcnt lgkmcnt(0)" ::: "memory");
;   const bf16x8 pa = (KS == 0) ? pa0 : (KS == 1) ? pa1 : (KS == 2) ? pa2 : pa3;
;   SBAR();
;   o[0] = MFMA32(pa, PKV(cur.l0, cur.h0), o[0]); SBAR(); sm1_chunk<KS * 4 + 0>(p0, p1); if constexpr (KS > 0) SM2_UNIT(2 * KS - 1); SBAR();
;   o[1] = MFMA32(pa, PKV(cur.l1, cur.h1), o[1]); SBAR(); sm1_chunk<KS * 4 + 1>(p0, p1);
;   if (dow) {
;     if constexpr (KS == 0) { asm volatile("s_waitcnt vmcnt(0)" ::: "memory"); *reinterpret_cast<bf16x8*>(sd.k0) = st.ks0; }
;     else if constexpr (KS == 1) *reinterpret_cast<bf16x8*>(sd.k1) = st.ks1;
;     else if constexpr (KS == 2) *reinterpret_cast<bf16x8*>(sd.v0) = st.vs0;
;     else *reinterpret_cast<bf16x8*>(sd.v1) = st.vs1;
;   }
;   SBAR();
;   o[2] = MFMA32(pa, PKV(cur.l2, cur.h2), o[2]); SBAR(); sm1_chunk<KS * 4 + 2>(p0, p1); SM2_UNIT(2 * KS); SBAR();
;   o[3] = MFMA32(pa, PKV(cur.l3, cur.h3), o[3]); SBAR(); sm1_chunk<KS * 4 + 3>(p0, p1); SBAR();
;   if constexpr (!SAFE) { lacc = MFMA32(pa, ones, lacc); SBAR(); }
; }
; template <bool SAFE> ...
;   bf16x8 kb[8];
; #pragma unroll
;   for (int d0 = 0; d0 < 4; ++d0) { const int cb = (cb0 + d0 * 16 + hi * 8) * 2;
;     kb[2 * d0] = *reinterpret_cast<const bf16x8*>((const char*)Ks + KSWZ(r32, cb));
;     kb[2 * d0 + 1] = *reinterpret_cast<const bf16x8*>((const char*)Ks + KSWZ(32 + r32, cb)); }
;   VFrag fa, fb;
;   vfrag_issue<0>(fa, vb);
;   p0 = MFMA32(kb[0], qr[0], cinit); p1 = MFMA32(kb[1], qr[0], cinit);
; #pragma unroll
;   for (int d0 = 1; d0 < 4; ++d0) { p0 = MFMA32(kb[2 * d0], qr[d0], p0); p1 = MFMA32(kb[2 * d0 + 1], qr[d0], p1); }
;   SBAR();
;   unsigned a0, a1, b0, b1; ps = 0.f;
;   fused_ks<0, SAFE>(o, lacc, vb, fa, fb, p0, p1, ps, a0, a1, b0, b1, pa0, pa1, pa2, pa3, st, sd, dow, ones);
;   fused_ks<1, SAFE>(o, lacc, vb, fb, fa, p0, p1, ps, a0, a1, b0, b1, pa0, pa1, pa2, pa3, st, sd, dow, ones);
;   fused_ks<2, SAFE>(o, lacc, vb, fa, fb, p0, p1, ps, a0, a1, b0, b1, pa0, pa1, pa2, pa3, st, sd, dow, ones);
;   fused_ks<3, SAFE>(o, lacc, vb, fb, fa, p0, p1, ps, a0, a1, b0, b1, pa0, pa1, pa2, pa3, st, sd, dow, ones);
.LBB0_316:
	ds_read_b128 v[212:215], v77 offset:49152
	ds_read_b128 v[216:219], v77 offset:57344
	s_lshl_b32 s11, s10, 14
	s_add_i32 s8, s11, 0
	s_add_i32 s98, s7, 2
	s_min_i32 s98, s98, s64
	s_mul_i32 s98, s98, 0x60000
	s_add_u32 s98, s14, s98
	s_addc_u32 s99, s15, 0
	s_add_u32 s100, s98, 0x30000
	s_addc_u32 s101, s99, 0
	v_add_u32_e32 v78, s8, v209
	v_mfma_f32_32x32x16_bf16 v[112:127], v[68:71], v[132:135], v[80:95]
	v_add_u32_e32 v160, s8, v210
	v_lshl_add_u32 v194, s6, 14, v211
	s_lshl_b32 s9, s27, 14
	s_add_i32 s9, s9, 0
	s_mov_b32 s26, s27
	v_add_u32_e32 v76, s9, v207
	v_mfma_f32_32x32x16_bf16 v[96:111], v[72:75], v[132:135], v[80:95]
	ds_read_b128 v[68:71], v78 offset:49152
	ds_read_b128 v[72:75], v78 offset:57344
	v_add_u32_e32 v188, s9, v205
	v_add_u32_e32 v161, s9, v203
	v_add_u32_e32 v170, s9, v204
	v_mfma_f32_16x16x32_bf16 v[64:67], v[180:183], v[148:151], v[64:67]
	s_waitcnt lgkmcnt(3)
	v_mfma_f32_32x32x16_bf16 v[112:127], v[212:215], v[136:139], v[112:127]
	ds_read_b128 v[212:215], v160 offset:49152
	s_waitcnt vmcnt(3)
	ds_write_b128 v161, v[166:169] offset:49152
	global_load_dwordx4 v[166:169], v247, s[98:99] offset:1024
	s_waitcnt lgkmcnt(4)
	v_mfma_f32_32x32x16_bf16 v[96:111], v[216:219], v[136:139], v[96:111]
	ds_read_b128 v[216:219], v160 offset:57344
	v_add_u32_e32 v189, s9, v206
	v_add_u32_e32 v77, s9, v208
	v_mfma_f32_16x16x32_bf16 v[64:67], v[184:187], v[148:151], v[64:67]
	s_waitcnt lgkmcnt(4)
	v_mfma_f32_32x32x16_bf16 v[112:127], v[68:71], v[140:143], v[112:127]
	ds_read_b64_tr_b16 v[220:221], v194 offset:0
	ds_read_b64_tr_b16 v[222:223], v194 offset:0x800
	s_waitcnt vmcnt(3)
	ds_write_b128 v170, v[162:165] offset:49152
	global_load_dwordx4 v[162:165], v247, s[100:101] offset:1024
	v_mfma_f32_16x16x32_bf16 v[64:67], v[176:179], v[148:151], v[64:67]
	s_waitcnt lgkmcnt(6)
	v_mfma_f32_32x32x16_bf16 v[96:111], v[72:75], v[140:143], v[96:111]
	v_mfma_f32_16x16x32_bf16 v[64:67], v[172:175], v[148:151], v[64:67]
	s_waitcnt lgkmcnt(5)
	v_mfma_f32_32x32x16_bf16 v[112:127], v[212:215], v[144:147], v[112:127]
	ds_read_b64_tr_b16 v[212:213], v194 offset:0x200
	ds_read_b64_tr_b16 v[214:215], v194 offset:0xa00
	ds_read_b64_tr_b16 v[224:225], v194 offset:0x400
	ds_read_b64_tr_b16 v[226:227], v194 offset:0xc00
	ds_read_b64_tr_b16 v[228:229], v194 offset:0x600
	ds_read_b64_tr_b16 v[230:231], v194 offset:0xe00
	s_waitcnt lgkmcnt(7)
	v_mfma_f32_32x32x16_bf16 v[96:111], v[216:219], v[144:147], v[96:111]
	ds_read_b64_tr_b16 v[216:217], v194 offset:0x1000
	ds_read_b64_tr_b16 v[218:219], v194 offset:0x1800
	ds_read_b64_tr_b16 v[232:233], v194 offset:0x1200
	ds_read_b64_tr_b16 v[234:235], v194 offset:0x1a00
	ds_read_b64_tr_b16 v[236:237], v194 offset:0x1400
	ds_read_b64_tr_b16 v[238:239], v194 offset:0x1c00
	ds_read_b64_tr_b16 v[240:241], v194 offset:0x1600
	ds_read_b64_tr_b16 v[242:243], v194 offset:0x1e00
	s_nop 0
	v_mfma_f32_32x32x16_bf16 v[48:63], v[180:183], v[220:223], v[48:63]
	s_nop 0
	v_exp_f32_e32 v112, v112
	v_exp_f32_e32 v113, v113
	s_waitcnt lgkmcnt(12)
	v_mfma_f32_32x32x16_bf16 v[32:47], v[180:183], v[212:215], v[32:47]
	v_exp_f32_e32 v114, v114
	v_exp_f32_e32 v115, v115
	s_waitcnt lgkmcnt(10)
	v_mfma_f32_32x32x16_bf16 v[0:15], v[180:183], v[224:227], v[0:15]
	v_exp_f32_e32 v171, v116
	v_exp_f32_e32 v220, v117
	s_waitcnt lgkmcnt(8)
	v_mfma_f32_32x32x16_bf16 v[16:31], v[180:183], v[228:231], v[16:31]
	v_exp_f32_e32 v221, v118
	v_exp_f32_e32 v222, v119
	v_cvt_pk_bf16_f32 v180, v112, v113
	v_cvt_pk_bf16_f32 v181, v114, v115
	ds_read_b64_tr_b16 v[112:113], v194 offset:0x2000
	ds_read_b64_tr_b16 v[114:115], v194 offset:0x2800
	ds_read_b64_tr_b16 v[116:117], v194 offset:0x2200
	ds_read_b64_tr_b16 v[118:119], v194 offset:0x2a00
	ds_read_b64_tr_b16 v[248:249], v194 offset:0x2400
	ds_read_b64_tr_b16 v[250:251], v194 offset:0x2c00
	ds_read_b64_tr_b16 v[212:213], v194 offset:0x2600
	ds_read_b64_tr_b16 v[214:215], v194 offset:0x2e00
	s_waitcnt lgkmcnt(8)
	v_mfma_f32_32x32x16_bf16 v[48:63], v[184:187], v[216:219], v[48:63]
	v_cvt_pk_bf16_f32 v182, v171, v220
	v_cvt_pk_bf16_f32 v183, v221, v222
	v_exp_f32_e32 v120, v120
	v_exp_f32_e32 v121, v121
	v_mfma_f32_32x32x16_bf16 v[32:47], v[184:187], v[232:235], v[32:47]
	v_exp_f32_e32 v122, v122
	v_exp_f32_e32 v123, v123
	v_mfma_f32_32x32x16_bf16 v[0:15], v[184:187], v[236:239], v[0:15]
	v_exp_f32_e32 v160, v124
	v_exp_f32_e32 v161, v125
	v_mfma_f32_32x32x16_bf16 v[16:31], v[184:187], v[240:243], v[16:31]
	v_exp_f32_e32 v220, v126
	v_exp_f32_e32 v221, v127
	v_cvt_pk_bf16_f32 v184, v120, v121
	v_cvt_pk_bf16_f32 v185, v122, v123
	s_waitcnt lgkmcnt(0)
	s_barrier
; template <int KS, bool SAFE> __device__ __forceinline__ void fused_ks(f32x16* o, f32x16& lacc, int vb, const VFrag& cur, VFrag& nxt, f32x16& p0, f32x16& p1, float& ps, ...
;   if constexpr (KS < 3) { vfrag_issue<KS + 1>(nxt, vb); asm volatile("s_waitcnt lgkmcnt(8)" ::: "memory"); }
;   else asm volatile("s_waitcnt lgkmcnt(0)" ::: "memory");
;   const bf16x8 pa = (KS == 0) ? pa0 : (KS == 1) ? pa1 : (KS == 2) ? pa2 : pa3;
;   SBAR();
;   o[0] = MFMA32(pa, PKV(cur.l0, cur.h0), o[0]); SBAR(); sm1_chunk<KS * 4 + 0>(p0, p1); if constexpr (KS > 0) SM2_UNIT(2 * KS - 1); SBAR();
;   o[1] = MFMA32(pa, PKV(cur.l1, cur.h1), o[1]); SBAR(); sm1_chunk<KS * 4 + 1>(p0, p1);
;   if (dow) {
;     if constexpr (KS == 0) { asm volatile("s_waitcnt vmcnt(0)" ::: "memory"); *reinterpret_cast<bf16x8*>(sd.k0) = st.ks0; }
;     else if constexpr (KS == 1) *reinterpret_cast<bf16x8*>(sd.k1) = st.ks1;
;     else if constexpr (KS == 2) *reinterpret_cast<bf16x8*>(sd.v0) = st.vs0;
;     else *reinterpret_cast<bf16x8*>(sd.v1) = st.vs1;
;   }
;   SBAR();
;   o[2] = MFMA32(pa, PKV(cur.l2, cur.h2), o[2]); SBAR(); sm1_chunk<KS * 4 + 2>(p0, p1); SM2_UNIT(2 * KS); SBAR();
;   o[3] = MFMA32(pa, PKV(cur.l3, cur.h3), o[3]); SBAR(); sm1_chunk<KS * 4 + 3>(p0, p1); SBAR();
;   if constexpr (!SAFE) { lacc = MFMA32(pa, ones, lacc); SBAR(); }
; }
; template <bool SAFE> ...
;   bf16x8 kb[8];
; #pragma unroll
;   for (int d0 = 0; d0 < 4; ++d0) { const int cb = (cb0 + d0 * 16 + hi * 8) * 2;
;     kb[2 * d0] = *reinterpret_cast<const bf16x8*>((const char*)Ks + KSWZ(r32, cb));
;     kb[2 * d0 + 1] = *reinterpret_cast<const bf16x8*>((const char*)Ks + KSWZ(32 + r32, cb)); }
;   VFrag fa, fb;
;   vfrag_issue<0>(fa, vb);
;   p0 = MFMA32(kb[0], qr[0], cinit); p1 = MFMA32(kb[1], qr[0], cinit);
; #pragma unroll
;   for (int d0 = 1; d0 < 4; ++d0) { p0 = MFMA32(kb[2 * d0], qr[d0], p0); p1 = MFMA32(kb[2 * d0 + 1], qr[d0], p1); }
;   SBAR();
;   unsigned a0, a1, b0, b1; ps = 0.f;
;   fused_ks<0, SAFE>(o, lacc, vb, fa, fb, p0, p1, ps, a0, a1, b0, b1, pa0, pa1, pa2, pa3, st, sd, dow, ones);
;   fused_ks<1, SAFE>(o, lacc, vb, fb, fa, p0, p1, ps, a0, a1, b0, b1, pa0, pa1, pa2, pa3, st, sd, dow, ones);
;   fused_ks<2, SAFE>(o, lacc, vb, fa, fb, p0, p1, ps, a0, a1, b0, b1, pa0, pa1, pa2, pa3, st, sd, dow, ones);
;   fused_ks<3, SAFE>(o, lacc, vb, fb, fa, p0, p1, ps, a0, a1, b0, b1, pa0, pa1, pa2, pa3, st, sd, dow, ones);
	v_mfma_f32_32x32x16_bf16 v[48:63], v[176:179], v[112:115], v[48:63]
	ds_read_b128 v[68:71], v76 offset:49152
	ds_read_b128 v[72:75], v76 offset:57344
	ds_read_b64_tr_b16 v[120:121], v194 offset:0x3000
	ds_read_b64_tr_b16 v[122:123], v194 offset:0x3800
	ds_read_b64_tr_b16 v[124:125], v194 offset:0x3200
	ds_read_b64_tr_b16 v[126:127], v194 offset:0x3a00
	ds_read_b64_tr_b16 v[252:253], v194 offset:0x3400
	ds_read_b64_tr_b16 v[254:255], v194 offset:0x3c00
	ds_read_b64_tr_b16 v[216:217], v194 offset:0x3600
	ds_read_b64_tr_b16 v[218:219], v194 offset:0x3e00
	v_cvt_pk_bf16_f32 v186, v160, v161
	v_cvt_pk_bf16_f32 v187, v220, v221
	v_exp_f32_e32 v96, v96
	v_exp_f32_e32 v97, v97
	v_mfma_f32_32x32x16_bf16 v[32:47], v[176:179], v[116:119], v[32:47]
	v_exp_f32_e32 v98, v98
	v_exp_f32_e32 v99, v99
	s_waitcnt vmcnt(3)
	ds_write_b128 v188, v[156:159]
	global_load_dwordx4 v[156:159], v247, s[98:99] offset:2048
	v_mfma_f32_32x32x16_bf16 v[0:15], v[176:179], v[248:251], v[0:15]
	v_exp_f32_e32 v100, v100
	v_exp_f32_e32 v101, v101
	v_mfma_f32_32x32x16_bf16 v[16:31], v[176:179], v[212:215], v[16:31]
	v_cvt_pk_bf16_f32 v176, v96, v97
	v_cvt_pk_bf16_f32 v177, v98, v99
	v_exp_f32_e32 v96, v102
	v_exp_f32_e32 v97, v103
	s_waitcnt lgkmcnt(1)
	v_mfma_f32_32x32x16_bf16 v[48:63], v[172:175], v[120:123], v[48:63]
	v_cvt_pk_bf16_f32 v178, v100, v101
	v_cvt_pk_bf16_f32 v179, v96, v97
	v_exp_f32_e32 v98, v104
	v_exp_f32_e32 v99, v105
	v_mfma_f32_32x32x16_bf16 v[32:47], v[172:175], v[124:127], v[32:47]
	v_exp_f32_e32 v96, v106
	v_exp_f32_e32 v97, v107
	s_waitcnt vmcnt(3)
	ds_write_b128 v189, v[152:155]
	global_load_dwordx4 v[152:155], v247, s[100:101] offset:2048
	v_mfma_f32_32x32x16_bf16 v[0:15], v[172:175], v[252:255], v[0:15]
	v_exp_f32_e32 v100, v108
	v_exp_f32_e32 v101, v109
	v_mfma_f32_32x32x16_bf16 v[16:31], v[172:175], v[216:219], v[16:31]
	v_cvt_pk_bf16_f32 v172, v98, v99
	v_cvt_pk_bf16_f32 v173, v96, v97
	v_exp_f32_e32 v102, v110
	v_exp_f32_e32 v103, v111
	v_cvt_pk_bf16_f32 v174, v100, v101
	v_cvt_pk_bf16_f32 v175, v102, v103
	s_add_i32 s7, s7, 1
	s_mov_b32 s27, s6
	s_mov_b32 s6, s10
	s_cmp_lg_u32 s55, s7
	s_mov_b32 s10, s26
	s_cbranch_scc1 .LBB0_316
; #define MFMA32(a, b, c) __builtin_amdgcn_mfma_f32_32x32x16_bf16(a, b, c, 0, 0, 0)
; template <bool SAFE>
; __device__ __forceinline__ void diff_core(const bf16* __restrict__ Kh, const bf16* __restrict__ Vh, const int NT, const bf16x8* qr, char* lds,
;                                           const int wid, const int lane_unused, f32x16* o, f32x16& lacc, float& l_reg) {
;     ...
;   pv_d0(o, vb0 + bp * SHM_V, pa0, pa1, pa2, pa3);
;   if constexpr (!SAFE) {
;     lacc = MFMA32(pa0, ones, lacc); lacc = MFMA32(pa1, ones, lacc); lacc = MFMA32(pa2, ones, lacc); lacc = MFMA32(pa3, ones, lacc); }
; __device__ __forceinline__ void diff_attn_item(const bf16* __restrict__ qkv, bf16* __restrict__ mix, const float* __restrict__ dg,
;                                int tok0  , int key0  , int seq, int head, float lam, float oscale, const int W) {
;     ...
;     bool bad = (FORCE_SAFE != 0);
; #pragma unroll
;     for (int r = 0; r < 16; ++r) bad = bad || !(lacc[r] < 1.0e30f);
;     if (lane == 0) flag_l[wid] = __any(bad) ? 1 : 0;
	v_mov_b32_e32 v160, v180
	v_mov_b32_e32 v161, v181
	v_mov_b32_e32 v170, v184
	v_mov_b32_e32 v171, v185
	v_mov_b32_e32 v180, v176
	v_mov_b32_e32 v181, v177
	v_mov_b32_e32 v188, v172
	v_mov_b32_e32 v189, v173
	s_waitcnt vmcnt(0)
	v_add_u32_e32 v168, s11, v211
	ds_read_b64_tr_b16 v[80:81], v168 offset:0
	ds_read_b64_tr_b16 v[82:83], v168 offset:0x800
	ds_read_b64_tr_b16 v[84:85], v168 offset:0x1000
	ds_read_b64_tr_b16 v[86:87], v168 offset:0x1800
	ds_read_b64_tr_b16 v[88:89], v168 offset:0x2000
	ds_read_b64_tr_b16 v[90:91], v168 offset:0x2800
	ds_read_b64_tr_b16 v[92:93], v168 offset:0x3000
	ds_read_b64_tr_b16 v[94:95], v168 offset:0x3800
	s_waitcnt lgkmcnt(0)
	s_waitcnt vmcnt(0)
	v_mov_b32_e32 v162, v182
	v_mov_b32_e32 v163, v183
	v_mov_b32_e32 v172, v186
	v_mov_b32_e32 v173, v187
	v_mov_b32_e32 v182, v178
	v_mov_b32_e32 v183, v179
	v_mov_b32_e32 v190, v174
	v_mov_b32_e32 v191, v175
	ds_read_b64_tr_b16 v[96:97], v168 offset:0x200
	ds_read_b64_tr_b16 v[98:99], v168 offset:0xa00
	ds_read_b64_tr_b16 v[100:101], v168 offset:0x1200
	ds_read_b64_tr_b16 v[102:103], v168 offset:0x1a00
	ds_read_b64_tr_b16 v[104:105], v168 offset:0x2200
	ds_read_b64_tr_b16 v[106:107], v168 offset:0x2a00
	ds_read_b64_tr_b16 v[108:109], v168 offset:0x3200
	ds_read_b64_tr_b16 v[110:111], v168 offset:0x3a00
	s_waitcnt lgkmcnt(0)
	ds_read_b64_tr_b16 v[112:113], v168 offset:0x400
	ds_read_b64_tr_b16 v[114:115], v168 offset:0xc00
	ds_read_b64_tr_b16 v[116:117], v168 offset:0x1400
	ds_read_b64_tr_b16 v[118:119], v168 offset:0x1c00
	ds_read_b64_tr_b16 v[120:121], v168 offset:0x2400
	ds_read_b64_tr_b16 v[122:123], v168 offset:0x2c00
	ds_read_b64_tr_b16 v[124:125], v168 offset:0x3400
	ds_read_b64_tr_b16 v[126:127], v168 offset:0x3c00
	s_waitcnt lgkmcnt(0)
	ds_read_b64_tr_b16 v[152:153], v168 offset:0x600
	ds_read_b64_tr_b16 v[154:155], v168 offset:0xe00
	ds_read_b64_tr_b16 v[156:157], v168 offset:0x1600
	ds_read_b64_tr_b16 v[158:159], v168 offset:0x1e00
	ds_read_b64_tr_b16 v[164:165], v168 offset:0x2600
	ds_read_b64_tr_b16 v[166:167], v168 offset:0x2e00
	ds_read_b64_tr_b16 v[174:175], v168 offset:0x3600
	ds_read_b64_tr_b16 v[176:177], v168 offset:0x3e00
	s_waitcnt lgkmcnt(0)
	v_mfma_f32_16x16x32_bf16 v[64:67], v[160:163], v[148:151], v[64:67]
	v_cmp_eq_u32_e32 vcc, 0, v200
	v_mfma_f32_32x32x16_bf16 v[48:63], v[160:163], v[80:83], v[48:63]
	v_mfma_f32_32x32x16_bf16 v[32:47], v[160:163], v[96:99], v[32:47]
	v_mfma_f32_32x32x16_bf16 v[0:15], v[160:163], v[112:115], v[0:15]
	v_mfma_f32_32x32x16_bf16 v[16:31], v[160:163], v[152:155], v[16:31]
	v_mfma_f32_16x16x32_bf16 v[64:67], v[170:173], v[148:151], v[64:67]
	v_mfma_f32_32x32x16_bf16 v[48:63], v[170:173], v[84:87], v[48:63]
	v_mfma_f32_32x32x16_bf16 v[32:47], v[170:173], v[100:103], v[32:47]
	v_mfma_f32_32x32x16_bf16 v[0:15], v[170:173], v[116:119], v[0:15]
	v_mfma_f32_32x32x16_bf16 v[16:31], v[170:173], v[156:159], v[16:31]
	v_mfma_f32_16x16x32_bf16 v[64:67], v[180:183], v[148:151], v[64:67]
	v_mfma_f32_32x32x16_bf16 v[48:63], v[180:183], v[88:91], v[48:63]
	v_mfma_f32_32x32x16_bf16 v[32:47], v[180:183], v[104:107], v[32:47]
	v_mfma_f32_32x32x16_bf16 v[0:15], v[180:183], v[120:123], v[0:15]
	v_mfma_f32_32x32x16_bf16 v[16:31], v[180:183], v[164:167], v[16:31]
	v_mfma_f32_16x16x32_bf16 v[64:67], v[188:191], v[148:151], v[64:67]
	v_mfma_f32_32x32x16_bf16 v[48:63], v[188:191], v[92:95], v[48:63]
	v_mfma_f32_32x32x16_bf16 v[32:47], v[188:191], v[108:111], v[32:47]
	v_mfma_f32_32x32x16_bf16 v[0:15], v[188:191], v[124:127], v[0:15]
	v_mfma_f32_32x32x16_bf16 v[16:31], v[188:191], v[174:177], v[16:31]
	v_and_b32_e32 v248, 15, v200
	v_lshrrev_b32_e32 v249, 4, v200
	v_and_b32_e32 v250, 1, v200
	v_lshlrev_b32_e32 v249, 4, v249
	v_lshl_add_u32 v249, v250, 6, v249
	v_add_u32_e32 v249, s62, v249
	v_cmp_gt_u32_e64 s[98:99], 2, v248
	v_lshl_add_u32 v250, v198, 4, s62
	s_nop 7
	s_and_saveexec_b64 s[100:101], s[98:99]
	ds_write_b128 v249, v[64:67]
	s_mov_b64 exec, s[100:101]
	s_waitcnt lgkmcnt(0)
	ds_read_b128 v[64:67], v250
	ds_read_b128 v[68:71], v250 offset:32
	ds_read_b128 v[72:75], v250 offset:64
	ds_read_b128 v[76:79], v250 offset:96
	s_waitcnt lgkmcnt(0)
	s_and_saveexec_b64 s[10:11], vcc
	s_cbranch_execz .LBB0_319
	s_nop 5
	v_cmp_ngt_f32_e32 vcc, s44, v64
	v_cmp_ngt_f32_e64 s[6:7], s44, v65
	s_or_b64 s[6:7], vcc, s[6:7]
	v_cmp_ngt_f32_e32 vcc, s44, v66
	s_or_b64 s[6:7], s[6:7], vcc
	v_cmp_ngt_f32_e32 vcc, s44, v67
	s_or_b64 s[6:7], s[6:7], vcc
	v_cmp_ngt_f32_e32 vcc, s44, v68
	s_or_b64 s[6:7], s[6:7], vcc
	v_cmp_ngt_f32_e32 vcc, s44, v69
	s_or_b64 s[6:7], s[6:7], vcc
	v_cmp_ngt_f32_e32 vcc, s44, v70
	s_or_b64 s[6:7], s[6:7], vcc
	v_cmp_ngt_f32_e32 vcc, s44, v71
	s_or_b64 s[6:7], s[6:7], vcc
	v_cmp_ngt_f32_e32 vcc, s44, v72
	s_or_b64 s[6:7], s[6:7], vcc
	v_cmp_ngt_f32_e32 vcc, s44, v73
	s_or_b64 s[6:7], s[6:7], vcc
	v_cmp_ngt_f32_e32 vcc, s44, v74
	s_or_b64 s[6:7], s[6:7], vcc
	v_cmp_ngt_f32_e32 vcc, s44, v75
	s_or_b64 s[6:7], s[6:7], vcc
	v_cmp_ngt_f32_e32 vcc, s44, v76
	s_or_b64 s[6:7], s[6:7], vcc
	v_cmp_ngt_f32_e32 vcc, s44, v77
	s_or_b64 s[6:7], s[6:7], vcc
	v_cmp_ngt_f32_e32 vcc, s44, v78
	s_or_b64 s[6:7], s[6:7], vcc
	v_cmp_ngt_f32_e32 vcc, s44, v79
	s_or_b64 s[6:7], s[6:7], vcc
	v_cndmask_b32_e64 v80, 0, 1, s[6:7]
	v_cmp_ne_u32_e32 vcc, 0, v80
	s_cmp_lg_u64 vcc, 0
	s_cselect_b64 s[6:7], -1, 0
	v_cndmask_b32_e64 v80, 0, 1, s[6:7]
	v_readlane_b32 s6, v246, 17
	s_nop 1
	v_mov_b32_e32 v81, s6
	ds_write_b32 v81, v80
